# prologue phase rebalanced: workgroups 0..127 (which own the extra weight-conversion tiles) skip the hb/sum-square row loop, workgroups 128..255 do two batches of 8 rows with all loads in flight
# speedup vs baseline: 1.0030x; 1.0030x over previous
; DI void st_bf4(bf16_t* p, f32x4 v) { u32x2 w; w.x = pk2(v[0], v[1]); w.y = pk2(v[2], v[3]); *(u32x2*)p = w; }
;     DI bf16_t* hb() const { return (bf16_t*)(ws + WS_HB); }
;     DI float* ssqh() const { return (float*)(ws + WS_SSQH); }
;     DI const float* gin(int i) const { return (const float*)(const __attribute__((address_space(1))) float*)kp->in[i]; }
; DI void phase_prep(Frame& F) {
;     ...
;     for (int row = F.gw; row < M; row += F.ngw) {
;         const f32x4* xr = (const f32x4*)(F.gin(0) + (size_t)row * DM) + F.lane; float s = 0.f;
; #pragma unroll
;         for (int j = 0; j < 4; ++j) { f32x4 v = xr[64 * j]; s += (v[0] * v[0] + v[1] * v[1]) + (v[2] * v[2] + v[3] * v[3]);
;             st_bf4(F.hb() + (size_t)row * DM + 4 * (F.lane + 64 * j), v); }
;         s = wave_sum(s);
;         if (F.lane < 16) F.ssqh()[(size_t)row * 16 + F.lane] = F.lane == 0 ? s : 0.f;
.LBB0_2080:
	s_cmp_lt_u32 s2, 128
	s_cbranch_scc1 .LBB0_2082
	v_readlane_b32 s16, v254, 24
	v_readlane_b32 s17, v254, 25
	v_readlane_b32 s44, v254, 22
	v_readlane_b32 s45, v254, 23
	v_readlane_b32 s10, v254, 20
	v_readlane_b32 s11, v254, 21
	v_lshl_add_u64 v[32:33], s[76:77], 0, v[6:7]
	s_mov_b32 s24, 0xcd10000
	s_mov_b32 s25, 0
	v_lshl_add_u64 v[32:33], v[32:33], 0, s[24:25]
	v_lshl_add_u64 v[210:211], s[76:77], 0, v[4:5]
	global_load_dwordx4 v[36:39], v[8:9], off offset:-3072
	global_load_dwordx4 v[40:43], v[8:9], off offset:-2048
	global_load_dwordx4 v[44:47], v[8:9], off offset:-1024
	global_load_dwordx4 v[48:51], v[8:9], off
	v_lshl_add_u64 v[8:9], v[8:9], 0, s[16:17]
	global_load_dwordx4 v[52:55], v[8:9], off offset:-3072
	global_load_dwordx4 v[56:59], v[8:9], off offset:-2048
	global_load_dwordx4 v[60:63], v[8:9], off offset:-1024
	global_load_dwordx4 v[64:67], v[8:9], off
	v_lshl_add_u64 v[8:9], v[8:9], 0, s[16:17]
	global_load_dwordx4 v[68:71], v[8:9], off offset:-3072
	global_load_dwordx4 v[72:75], v[8:9], off offset:-2048
	global_load_dwordx4 v[76:79], v[8:9], off offset:-1024
	global_load_dwordx4 v[80:83], v[8:9], off
	v_lshl_add_u64 v[8:9], v[8:9], 0, s[16:17]
	global_load_dwordx4 v[84:87], v[8:9], off offset:-3072
	global_load_dwordx4 v[88:91], v[8:9], off offset:-2048
	global_load_dwordx4 v[92:95], v[8:9], off offset:-1024
	global_load_dwordx4 v[96:99], v[8:9], off
	v_lshl_add_u64 v[8:9], v[8:9], 0, s[16:17]
	global_load_dwordx4 v[100:103], v[8:9], off offset:-3072
	global_load_dwordx4 v[104:107], v[8:9], off offset:-2048
	global_load_dwordx4 v[108:111], v[8:9], off offset:-1024
	global_load_dwordx4 v[112:115], v[8:9], off
	v_lshl_add_u64 v[8:9], v[8:9], 0, s[16:17]
	global_load_dwordx4 v[116:119], v[8:9], off offset:-3072
	global_load_dwordx4 v[120:123], v[8:9], off offset:-2048
	global_load_dwordx4 v[124:127], v[8:9], off offset:-1024
	global_load_dwordx4 v[128:131], v[8:9], off
	v_lshl_add_u64 v[8:9], v[8:9], 0, s[16:17]
	global_load_dwordx4 v[132:135], v[8:9], off offset:-3072
	global_load_dwordx4 v[188:191], v[8:9], off offset:-2048
	global_load_dwordx4 v[192:195], v[8:9], off offset:-1024
	global_load_dwordx4 v[196:199], v[8:9], off
	v_lshl_add_u64 v[8:9], v[8:9], 0, s[16:17]
	global_load_dwordx4 v[200:203], v[8:9], off offset:-3072
	global_load_dwordx4 v[204:207], v[8:9], off offset:-2048
	global_load_dwordx4 v[236:239], v[8:9], off offset:-1024
	global_load_dwordx4 v[240:243], v[8:9], off
	s_waitcnt vmcnt(28)
	v_mul_f32_e32 v0, v37, v37
	v_mul_f32_e32 v3, v39, v39
	v_fmac_f32_e32 v0, v36, v36
	v_fmac_f32_e32 v3, v38, v38
	v_add_f32_e32 v16, v0, v3
	v_mul_f32_e32 v0, v41, v41
	v_mul_f32_e32 v3, v43, v43
	v_fmac_f32_e32 v0, v40, v40
	v_fmac_f32_e32 v3, v42, v42
	v_add_f32_e32 v0, v0, v3
	v_add_f32_e32 v16, v16, v0
	v_mul_f32_e32 v0, v45, v45
	v_mul_f32_e32 v3, v47, v47
	v_fmac_f32_e32 v0, v44, v44
	v_fmac_f32_e32 v3, v46, v46
	v_add_f32_e32 v0, v0, v3
	v_add_f32_e32 v16, v16, v0
	v_mul_f32_e32 v0, v49, v49
	v_mul_f32_e32 v3, v51, v51
	v_fmac_f32_e32 v0, v48, v48
	v_fmac_f32_e32 v3, v50, v50
	v_add_f32_e32 v0, v0, v3
	v_add_f32_e32 v16, v16, v0
	v_cvt_pk_bf16_f32 v36, v36, v37
	v_cvt_pk_bf16_f32 v37, v38, v39
	v_cvt_pk_bf16_f32 v40, v40, v41
	v_cvt_pk_bf16_f32 v41, v42, v43
	v_cvt_pk_bf16_f32 v44, v44, v45
	v_cvt_pk_bf16_f32 v45, v46, v47
	v_cvt_pk_bf16_f32 v48, v48, v49
	v_cvt_pk_bf16_f32 v49, v50, v51
	global_store_dwordx2 v[32:33], v[36:37], off
	global_store_dwordx2 v[32:33], v[40:41], off offset:512
	global_store_dwordx2 v[32:33], v[44:45], off offset:1024
	global_store_dwordx2 v[32:33], v[48:49], off offset:1536
	v_lshl_add_u64 v[32:33], v[32:33], 0, s[44:45]
	s_waitcnt vmcnt(28)
	v_mul_f32_e32 v0, v53, v53
	v_mul_f32_e32 v3, v55, v55
	v_fmac_f32_e32 v0, v52, v52
	v_fmac_f32_e32 v3, v54, v54
	v_add_f32_e32 v17, v0, v3
	v_mul_f32_e32 v0, v57, v57
	v_mul_f32_e32 v3, v59, v59
	v_fmac_f32_e32 v0, v56, v56
	v_fmac_f32_e32 v3, v58, v58
	v_add_f32_e32 v0, v0, v3
	v_add_f32_e32 v17, v17, v0
	v_mul_f32_e32 v0, v61, v61
	v_mul_f32_e32 v3, v63, v63
	v_fmac_f32_e32 v0, v60, v60
	v_fmac_f32_e32 v3, v62, v62
	v_add_f32_e32 v0, v0, v3
	v_add_f32_e32 v17, v17, v0
	v_mul_f32_e32 v0, v65, v65
	v_mul_f32_e32 v3, v67, v67
	v_fmac_f32_e32 v0, v64, v64
	v_fmac_f32_e32 v3, v66, v66
	v_add_f32_e32 v0, v0, v3
	v_add_f32_e32 v17, v17, v0
	v_cvt_pk_bf16_f32 v52, v52, v53
	v_cvt_pk_bf16_f32 v53, v54, v55
	v_cvt_pk_bf16_f32 v56, v56, v57
	v_cvt_pk_bf16_f32 v57, v58, v59
	v_cvt_pk_bf16_f32 v60, v60, v61
	v_cvt_pk_bf16_f32 v61, v62, v63
	v_cvt_pk_bf16_f32 v64, v64, v65
	v_cvt_pk_bf16_f32 v65, v66, v67
	global_store_dwordx2 v[32:33], v[52:53], off
	global_store_dwordx2 v[32:33], v[56:57], off offset:512
	global_store_dwordx2 v[32:33], v[60:61], off offset:1024
	global_store_dwordx2 v[32:33], v[64:65], off offset:1536
	v_lshl_add_u64 v[32:33], v[32:33], 0, s[44:45]
	s_waitcnt vmcnt(28)
	v_mul_f32_e32 v0, v69, v69
	v_mul_f32_e32 v3, v71, v71
	v_fmac_f32_e32 v0, v68, v68
	v_fmac_f32_e32 v3, v70, v70
	v_add_f32_e32 v18, v0, v3
	v_mul_f32_e32 v0, v73, v73
	v_mul_f32_e32 v3, v75, v75
	v_fmac_f32_e32 v0, v72, v72
	v_fmac_f32_e32 v3, v74, v74
	v_add_f32_e32 v0, v0, v3
	v_add_f32_e32 v18, v18, v0
	v_mul_f32_e32 v0, v77, v77
	v_mul_f32_e32 v3, v79, v79
	v_fmac_f32_e32 v0, v76, v76
	v_fmac_f32_e32 v3, v78, v78
	v_add_f32_e32 v0, v0, v3
	v_add_f32_e32 v18, v18, v0
	v_mul_f32_e32 v0, v81, v81
	v_mul_f32_e32 v3, v83, v83
	v_fmac_f32_e32 v0, v80, v80
	v_fmac_f32_e32 v3, v82, v82
	v_add_f32_e32 v0, v0, v3
	v_add_f32_e32 v18, v18, v0
	v_cvt_pk_bf16_f32 v68, v68, v69
	v_cvt_pk_bf16_f32 v69, v70, v71
	v_cvt_pk_bf16_f32 v72, v72, v73
	v_cvt_pk_bf16_f32 v73, v74, v75
	v_cvt_pk_bf16_f32 v76, v76, v77
	v_cvt_pk_bf16_f32 v77, v78, v79
	v_cvt_pk_bf16_f32 v80, v80, v81
	v_cvt_pk_bf16_f32 v81, v82, v83
	global_store_dwordx2 v[32:33], v[68:69], off
	global_store_dwordx2 v[32:33], v[72:73], off offset:512
	global_store_dwordx2 v[32:33], v[76:77], off offset:1024
	global_store_dwordx2 v[32:33], v[80:81], off offset:1536
	v_lshl_add_u64 v[32:33], v[32:33], 0, s[44:45]
	s_waitcnt vmcnt(28)
; DI void st_bf4(bf16_t* p, f32x4 v) { u32x2 w; w.x = pk2(v[0], v[1]); w.y = pk2(v[2], v[3]); *(u32x2*)p = w; }
;     DI bf16_t* hb() const { return (bf16_t*)(ws + WS_HB); }
;     DI float* ssqh() const { return (float*)(ws + WS_SSQH); }
;     DI const float* gin(int i) const { return (const float*)(const __attribute__((address_space(1))) float*)kp->in[i]; }
; DI void phase_prep(Frame& F) {
;     ...
;     for (int row = F.gw; row < M; row += F.ngw) {
;         const f32x4* xr = (const f32x4*)(F.gin(0) + (size_t)row * DM) + F.lane; float s = 0.f;
; #pragma unroll
;         for (int j = 0; j < 4; ++j) { f32x4 v = xr[64 * j]; s += (v[0] * v[0] + v[1] * v[1]) + (v[2] * v[2] + v[3] * v[3]);
;             st_bf4(F.hb() + (size_t)row * DM + 4 * (F.lane + 64 * j), v); }
;         s = wave_sum(s);
;         if (F.lane < 16) F.ssqh()[(size_t)row * 16 + F.lane] = F.lane == 0 ? s : 0.f;
	v_mul_f32_e32 v0, v85, v85
	v_mul_f32_e32 v3, v87, v87
	v_fmac_f32_e32 v0, v84, v84
	v_fmac_f32_e32 v3, v86, v86
	v_add_f32_e32 v19, v0, v3
	v_mul_f32_e32 v0, v89, v89
	v_mul_f32_e32 v3, v91, v91
	v_fmac_f32_e32 v0, v88, v88
	v_fmac_f32_e32 v3, v90, v90
	v_add_f32_e32 v0, v0, v3
	v_add_f32_e32 v19, v19, v0
	v_mul_f32_e32 v0, v93, v93
	v_mul_f32_e32 v3, v95, v95
	v_fmac_f32_e32 v0, v92, v92
	v_fmac_f32_e32 v3, v94, v94
	v_add_f32_e32 v0, v0, v3
	v_add_f32_e32 v19, v19, v0
	v_mul_f32_e32 v0, v97, v97
	v_mul_f32_e32 v3, v99, v99
	v_fmac_f32_e32 v0, v96, v96
	v_fmac_f32_e32 v3, v98, v98
	v_add_f32_e32 v0, v0, v3
	v_add_f32_e32 v19, v19, v0
	v_cvt_pk_bf16_f32 v84, v84, v85
	v_cvt_pk_bf16_f32 v85, v86, v87
	v_cvt_pk_bf16_f32 v88, v88, v89
	v_cvt_pk_bf16_f32 v89, v90, v91
	v_cvt_pk_bf16_f32 v92, v92, v93
	v_cvt_pk_bf16_f32 v93, v94, v95
	v_cvt_pk_bf16_f32 v96, v96, v97
	v_cvt_pk_bf16_f32 v97, v98, v99
	global_store_dwordx2 v[32:33], v[84:85], off
	global_store_dwordx2 v[32:33], v[88:89], off offset:512
	global_store_dwordx2 v[32:33], v[92:93], off offset:1024
	global_store_dwordx2 v[32:33], v[96:97], off offset:1536
	v_lshl_add_u64 v[32:33], v[32:33], 0, s[44:45]
	s_waitcnt vmcnt(28)
	v_mul_f32_e32 v0, v101, v101
	v_mul_f32_e32 v3, v103, v103
	v_fmac_f32_e32 v0, v100, v100
	v_fmac_f32_e32 v3, v102, v102
	v_add_f32_e32 v20, v0, v3
	v_mul_f32_e32 v0, v105, v105
	v_mul_f32_e32 v3, v107, v107
	v_fmac_f32_e32 v0, v104, v104
	v_fmac_f32_e32 v3, v106, v106
	v_add_f32_e32 v0, v0, v3
	v_add_f32_e32 v20, v20, v0
	v_mul_f32_e32 v0, v109, v109
	v_mul_f32_e32 v3, v111, v111
	v_fmac_f32_e32 v0, v108, v108
	v_fmac_f32_e32 v3, v110, v110
	v_add_f32_e32 v0, v0, v3
	v_add_f32_e32 v20, v20, v0
	v_mul_f32_e32 v0, v113, v113
	v_mul_f32_e32 v3, v115, v115
	v_fmac_f32_e32 v0, v112, v112
	v_fmac_f32_e32 v3, v114, v114
	v_add_f32_e32 v0, v0, v3
	v_add_f32_e32 v20, v20, v0
	v_cvt_pk_bf16_f32 v100, v100, v101
	v_cvt_pk_bf16_f32 v101, v102, v103
	v_cvt_pk_bf16_f32 v104, v104, v105
	v_cvt_pk_bf16_f32 v105, v106, v107
	v_cvt_pk_bf16_f32 v108, v108, v109
	v_cvt_pk_bf16_f32 v109, v110, v111
	v_cvt_pk_bf16_f32 v112, v112, v113
	v_cvt_pk_bf16_f32 v113, v114, v115
	global_store_dwordx2 v[32:33], v[100:101], off
	global_store_dwordx2 v[32:33], v[104:105], off offset:512
	global_store_dwordx2 v[32:33], v[108:109], off offset:1024
	global_store_dwordx2 v[32:33], v[112:113], off offset:1536
	v_lshl_add_u64 v[32:33], v[32:33], 0, s[44:45]
	s_waitcnt vmcnt(28)
	v_mul_f32_e32 v0, v117, v117
	v_mul_f32_e32 v3, v119, v119
	v_fmac_f32_e32 v0, v116, v116
	v_fmac_f32_e32 v3, v118, v118
	v_add_f32_e32 v21, v0, v3
	v_mul_f32_e32 v0, v121, v121
	v_mul_f32_e32 v3, v123, v123
	v_fmac_f32_e32 v0, v120, v120
	v_fmac_f32_e32 v3, v122, v122
	v_add_f32_e32 v0, v0, v3
	v_add_f32_e32 v21, v21, v0
	v_mul_f32_e32 v0, v125, v125
	v_mul_f32_e32 v3, v127, v127
	v_fmac_f32_e32 v0, v124, v124
	v_fmac_f32_e32 v3, v126, v126
	v_add_f32_e32 v0, v0, v3
	v_add_f32_e32 v21, v21, v0
	v_mul_f32_e32 v0, v129, v129
	v_mul_f32_e32 v3, v131, v131
	v_fmac_f32_e32 v0, v128, v128
	v_fmac_f32_e32 v3, v130, v130
	v_add_f32_e32 v0, v0, v3
	v_add_f32_e32 v21, v21, v0
	v_cvt_pk_bf16_f32 v116, v116, v117
	v_cvt_pk_bf16_f32 v117, v118, v119
	v_cvt_pk_bf16_f32 v120, v120, v121
	v_cvt_pk_bf16_f32 v121, v122, v123
	v_cvt_pk_bf16_f32 v124, v124, v125
	v_cvt_pk_bf16_f32 v125, v126, v127
	v_cvt_pk_bf16_f32 v128, v128, v129
	v_cvt_pk_bf16_f32 v129, v130, v131
	global_store_dwordx2 v[32:33], v[116:117], off
	global_store_dwordx2 v[32:33], v[120:121], off offset:512
	global_store_dwordx2 v[32:33], v[124:125], off offset:1024
	global_store_dwordx2 v[32:33], v[128:129], off offset:1536
	v_lshl_add_u64 v[32:33], v[32:33], 0, s[44:45]
	s_waitcnt vmcnt(28)
	v_mul_f32_e32 v0, v133, v133
	v_mul_f32_e32 v3, v135, v135
	v_fmac_f32_e32 v0, v132, v132
	v_fmac_f32_e32 v3, v134, v134
	v_add_f32_e32 v22, v0, v3
	v_mul_f32_e32 v0, v189, v189
	v_mul_f32_e32 v3, v191, v191
	v_fmac_f32_e32 v0, v188, v188
	v_fmac_f32_e32 v3, v190, v190
	v_add_f32_e32 v0, v0, v3
	v_add_f32_e32 v22, v22, v0
	v_mul_f32_e32 v0, v193, v193
	v_mul_f32_e32 v3, v195, v195
	v_fmac_f32_e32 v0, v192, v192
	v_fmac_f32_e32 v3, v194, v194
	v_add_f32_e32 v0, v0, v3
	v_add_f32_e32 v22, v22, v0
	v_mul_f32_e32 v0, v197, v197
	v_mul_f32_e32 v3, v199, v199
	v_fmac_f32_e32 v0, v196, v196
	v_fmac_f32_e32 v3, v198, v198
	v_add_f32_e32 v0, v0, v3
	v_add_f32_e32 v22, v22, v0
	v_cvt_pk_bf16_f32 v132, v132, v133
	v_cvt_pk_bf16_f32 v133, v134, v135
	v_cvt_pk_bf16_f32 v188, v188, v189
	v_cvt_pk_bf16_f32 v189, v190, v191
	v_cvt_pk_bf16_f32 v192, v192, v193
	v_cvt_pk_bf16_f32 v193, v194, v195
	v_cvt_pk_bf16_f32 v196, v196, v197
	v_cvt_pk_bf16_f32 v197, v198, v199
	global_store_dwordx2 v[32:33], v[132:133], off
	global_store_dwordx2 v[32:33], v[188:189], off offset:512
	global_store_dwordx2 v[32:33], v[192:193], off offset:1024
	global_store_dwordx2 v[32:33], v[196:197], off offset:1536
	v_lshl_add_u64 v[32:33], v[32:33], 0, s[44:45]
	s_waitcnt vmcnt(28)
; DI void st_bf4(bf16_t* p, f32x4 v) { u32x2 w; w.x = pk2(v[0], v[1]); w.y = pk2(v[2], v[3]); *(u32x2*)p = w; }
;     DI bf16_t* hb() const { return (bf16_t*)(ws + WS_HB); }
;     DI float* ssqh() const { return (float*)(ws + WS_SSQH); }
;     DI const float* gin(int i) const { return (const float*)(const __attribute__((address_space(1))) float*)kp->in[i]; }
; DI float wave_sum(float v) {
; #pragma unroll
;     for (int o = 1; o < 64; o <<= 1) v += __shfl_xor(v, o);
;     return v;
; }
; DI void phase_prep(Frame& F) {
;     ...
;     for (int row = F.gw; row < M; row += F.ngw) {
;         const f32x4* xr = (const f32x4*)(F.gin(0) + (size_t)row * DM) + F.lane; float s = 0.f;
; #pragma unroll
;         for (int j = 0; j < 4; ++j) { f32x4 v = xr[64 * j]; s += (v[0] * v[0] + v[1] * v[1]) + (v[2] * v[2] + v[3] * v[3]);
;             st_bf4(F.hb() + (size_t)row * DM + 4 * (F.lane + 64 * j), v); }
;         s = wave_sum(s);
;         if (F.lane < 16) F.ssqh()[(size_t)row * 16 + F.lane] = F.lane == 0 ? s : 0.f;
	v_mul_f32_e32 v0, v201, v201
	v_mul_f32_e32 v3, v203, v203
	v_fmac_f32_e32 v0, v200, v200
	v_fmac_f32_e32 v3, v202, v202
	v_add_f32_e32 v23, v0, v3
	v_mul_f32_e32 v0, v205, v205
	v_mul_f32_e32 v3, v207, v207
	v_fmac_f32_e32 v0, v204, v204
	v_fmac_f32_e32 v3, v206, v206
	v_add_f32_e32 v0, v0, v3
	v_add_f32_e32 v23, v23, v0
	v_mul_f32_e32 v0, v237, v237
	v_mul_f32_e32 v3, v239, v239
	v_fmac_f32_e32 v0, v236, v236
	v_fmac_f32_e32 v3, v238, v238
	v_add_f32_e32 v0, v0, v3
	v_add_f32_e32 v23, v23, v0
	v_mul_f32_e32 v0, v241, v241
	v_mul_f32_e32 v3, v243, v243
	v_fmac_f32_e32 v0, v240, v240
	v_fmac_f32_e32 v3, v242, v242
	v_add_f32_e32 v0, v0, v3
	v_add_f32_e32 v23, v23, v0
	v_cvt_pk_bf16_f32 v200, v200, v201
	v_cvt_pk_bf16_f32 v201, v202, v203
	v_cvt_pk_bf16_f32 v204, v204, v205
	v_cvt_pk_bf16_f32 v205, v206, v207
	v_cvt_pk_bf16_f32 v236, v236, v237
	v_cvt_pk_bf16_f32 v237, v238, v239
	v_cvt_pk_bf16_f32 v240, v240, v241
	v_cvt_pk_bf16_f32 v241, v242, v243
	global_store_dwordx2 v[32:33], v[200:201], off
	global_store_dwordx2 v[32:33], v[204:205], off offset:512
	global_store_dwordx2 v[32:33], v[236:237], off offset:1024
	global_store_dwordx2 v[32:33], v[240:241], off offset:1536
	ds_bpermute_b32 v24, v10, v16
	ds_bpermute_b32 v25, v10, v17
	ds_bpermute_b32 v26, v10, v18
	ds_bpermute_b32 v27, v10, v19
	ds_bpermute_b32 v28, v10, v20
	ds_bpermute_b32 v29, v10, v21
	ds_bpermute_b32 v30, v10, v22
	ds_bpermute_b32 v31, v10, v23
	s_waitcnt lgkmcnt(0)
	v_add_f32_e32 v16, v16, v24
	v_add_f32_e32 v17, v17, v25
	v_add_f32_e32 v18, v18, v26
	v_add_f32_e32 v19, v19, v27
	v_add_f32_e32 v20, v20, v28
	v_add_f32_e32 v21, v21, v29
	v_add_f32_e32 v22, v22, v30
	v_add_f32_e32 v23, v23, v31
	ds_bpermute_b32 v24, v11, v16
	ds_bpermute_b32 v25, v11, v17
	ds_bpermute_b32 v26, v11, v18
	ds_bpermute_b32 v27, v11, v19
	ds_bpermute_b32 v28, v11, v20
	ds_bpermute_b32 v29, v11, v21
	ds_bpermute_b32 v30, v11, v22
	ds_bpermute_b32 v31, v11, v23
	s_waitcnt lgkmcnt(0)
	v_add_f32_e32 v16, v16, v24
	v_add_f32_e32 v17, v17, v25
	v_add_f32_e32 v18, v18, v26
	v_add_f32_e32 v19, v19, v27
	v_add_f32_e32 v20, v20, v28
	v_add_f32_e32 v21, v21, v29
	v_add_f32_e32 v22, v22, v30
	v_add_f32_e32 v23, v23, v31
	ds_bpermute_b32 v24, v12, v16
	ds_bpermute_b32 v25, v12, v17
	ds_bpermute_b32 v26, v12, v18
	ds_bpermute_b32 v27, v12, v19
	ds_bpermute_b32 v28, v12, v20
	ds_bpermute_b32 v29, v12, v21
	ds_bpermute_b32 v30, v12, v22
	ds_bpermute_b32 v31, v12, v23
	s_waitcnt lgkmcnt(0)
	v_add_f32_e32 v16, v16, v24
	v_add_f32_e32 v17, v17, v25
	v_add_f32_e32 v18, v18, v26
	v_add_f32_e32 v19, v19, v27
	v_add_f32_e32 v20, v20, v28
	v_add_f32_e32 v21, v21, v29
	v_add_f32_e32 v22, v22, v30
	v_add_f32_e32 v23, v23, v31
	ds_bpermute_b32 v24, v13, v16
	ds_bpermute_b32 v25, v13, v17
	ds_bpermute_b32 v26, v13, v18
	ds_bpermute_b32 v27, v13, v19
	ds_bpermute_b32 v28, v13, v20
	ds_bpermute_b32 v29, v13, v21
	ds_bpermute_b32 v30, v13, v22
	ds_bpermute_b32 v31, v13, v23
	s_waitcnt lgkmcnt(0)
	v_add_f32_e32 v16, v16, v24
	v_add_f32_e32 v17, v17, v25
	v_add_f32_e32 v18, v18, v26
	v_add_f32_e32 v19, v19, v27
	v_add_f32_e32 v20, v20, v28
	v_add_f32_e32 v21, v21, v29
	v_add_f32_e32 v22, v22, v30
	v_add_f32_e32 v23, v23, v31
	ds_bpermute_b32 v24, v14, v16
	ds_bpermute_b32 v25, v14, v17
	ds_bpermute_b32 v26, v14, v18
	ds_bpermute_b32 v27, v14, v19
	ds_bpermute_b32 v28, v14, v20
	ds_bpermute_b32 v29, v14, v21
	ds_bpermute_b32 v30, v14, v22
	ds_bpermute_b32 v31, v14, v23
	s_waitcnt lgkmcnt(0)
	v_add_f32_e32 v16, v16, v24
	v_add_f32_e32 v17, v17, v25
	v_add_f32_e32 v18, v18, v26
	v_add_f32_e32 v19, v19, v27
	v_add_f32_e32 v20, v20, v28
	v_add_f32_e32 v21, v21, v29
	v_add_f32_e32 v22, v22, v30
	v_add_f32_e32 v23, v23, v31
	ds_bpermute_b32 v24, v15, v16
	ds_bpermute_b32 v25, v15, v17
	ds_bpermute_b32 v26, v15, v18
	ds_bpermute_b32 v27, v15, v19
	ds_bpermute_b32 v28, v15, v20
	ds_bpermute_b32 v29, v15, v21
	ds_bpermute_b32 v30, v15, v22
	ds_bpermute_b32 v31, v15, v23
	s_waitcnt lgkmcnt(0)
	v_add_f32_e32 v16, v16, v24
	v_add_f32_e32 v17, v17, v25
	v_add_f32_e32 v18, v18, v26
	v_add_f32_e32 v19, v19, v27
	v_add_f32_e32 v20, v20, v28
	v_add_f32_e32 v21, v21, v29
	v_add_f32_e32 v22, v22, v30
	v_add_f32_e32 v23, v23, v31
	v_cndmask_b32_e64 v16, 0, v16, s[42:43]
	v_cndmask_b32_e64 v17, 0, v17, s[42:43]
	v_cndmask_b32_e64 v18, 0, v18, s[42:43]
	v_cndmask_b32_e64 v19, 0, v19, s[42:43]
	v_cndmask_b32_e64 v20, 0, v20, s[42:43]
	v_cndmask_b32_e64 v21, 0, v21, s[42:43]
	v_cndmask_b32_e64 v22, 0, v22, s[42:43]
	v_cndmask_b32_e64 v23, 0, v23, s[42:43]
	s_and_saveexec_b64 s[24:25], vcc
	global_store_dword v[210:211], v16, off
	v_lshl_add_u64 v[210:211], v[210:211], 0, s[10:11]
	global_store_dword v[210:211], v17, off
	v_lshl_add_u64 v[210:211], v[210:211], 0, s[10:11]
	global_store_dword v[210:211], v18, off
	v_lshl_add_u64 v[210:211], v[210:211], 0, s[10:11]
	global_store_dword v[210:211], v19, off
	v_lshl_add_u64 v[210:211], v[210:211], 0, s[10:11]
	global_store_dword v[210:211], v20, off
	v_lshl_add_u64 v[210:211], v[210:211], 0, s[10:11]
	global_store_dword v[210:211], v21, off
	v_lshl_add_u64 v[210:211], v[210:211], 0, s[10:11]
	global_store_dword v[210:211], v22, off
	v_lshl_add_u64 v[210:211], v[210:211], 0, s[10:11]
	global_store_dword v[210:211], v23, off
	s_or_b64 exec, exec, s[24:25]
	s_waitcnt vmcnt(0)
; DI void st_bf4(bf16_t* p, f32x4 v) { u32x2 w; w.x = pk2(v[0], v[1]); w.y = pk2(v[2], v[3]); *(u32x2*)p = w; }
;     DI bf16_t* hb() const { return (bf16_t*)(ws + WS_HB); }
;     DI float* ssqh() const { return (float*)(ws + WS_SSQH); }
;     DI const float* gin(int i) const { return (const float*)(const __attribute__((address_space(1))) float*)kp->in[i]; }
; DI void phase_prep(Frame& F) {
;     ...
;     for (int row = F.gw; row < M; row += F.ngw) {
;         const f32x4* xr = (const f32x4*)(F.gin(0) + (size_t)row * DM) + F.lane; float s = 0.f;
; #pragma unroll
;         for (int j = 0; j < 4; ++j) { f32x4 v = xr[64 * j]; s += (v[0] * v[0] + v[1] * v[1]) + (v[2] * v[2] + v[3] * v[3]);
;             st_bf4(F.hb() + (size_t)row * DM + 4 * (F.lane + 64 * j), v); }
;         s = wave_sum(s);
;         if (F.lane < 16) F.ssqh()[(size_t)row * 16 + F.lane] = F.lane == 0 ? s : 0.f;
	s_mov_b32 s24, 0xfc400000
	s_mov_b32 s25, 0xffffffff
	v_lshl_add_u64 v[8:9], v[8:9], 0, s[24:25]
	s_mov_b32 s24, 0xfe200000
	s_mov_b32 s25, 0xffffffff
	v_lshl_add_u64 v[32:33], v[32:33], 0, s[24:25]
	s_mov_b32 s24, 0xfff10000
	s_mov_b32 s25, 0xffffffff
	v_lshl_add_u64 v[210:211], v[210:211], 0, s[24:25]
	global_load_dwordx4 v[36:39], v[8:9], off offset:-3072
	global_load_dwordx4 v[40:43], v[8:9], off offset:-2048
	global_load_dwordx4 v[44:47], v[8:9], off offset:-1024
	global_load_dwordx4 v[48:51], v[8:9], off
	v_lshl_add_u64 v[8:9], v[8:9], 0, s[16:17]
	global_load_dwordx4 v[52:55], v[8:9], off offset:-3072
	global_load_dwordx4 v[56:59], v[8:9], off offset:-2048
	global_load_dwordx4 v[60:63], v[8:9], off offset:-1024
	global_load_dwordx4 v[64:67], v[8:9], off
	v_lshl_add_u64 v[8:9], v[8:9], 0, s[16:17]
	global_load_dwordx4 v[68:71], v[8:9], off offset:-3072
	global_load_dwordx4 v[72:75], v[8:9], off offset:-2048
	global_load_dwordx4 v[76:79], v[8:9], off offset:-1024
	global_load_dwordx4 v[80:83], v[8:9], off
	v_lshl_add_u64 v[8:9], v[8:9], 0, s[16:17]
	global_load_dwordx4 v[84:87], v[8:9], off offset:-3072
	global_load_dwordx4 v[88:91], v[8:9], off offset:-2048
	global_load_dwordx4 v[92:95], v[8:9], off offset:-1024
	global_load_dwordx4 v[96:99], v[8:9], off
	v_lshl_add_u64 v[8:9], v[8:9], 0, s[16:17]
	global_load_dwordx4 v[100:103], v[8:9], off offset:-3072
	global_load_dwordx4 v[104:107], v[8:9], off offset:-2048
	global_load_dwordx4 v[108:111], v[8:9], off offset:-1024
	global_load_dwordx4 v[112:115], v[8:9], off
	v_lshl_add_u64 v[8:9], v[8:9], 0, s[16:17]
	global_load_dwordx4 v[116:119], v[8:9], off offset:-3072
	global_load_dwordx4 v[120:123], v[8:9], off offset:-2048
	global_load_dwordx4 v[124:127], v[8:9], off offset:-1024
	global_load_dwordx4 v[128:131], v[8:9], off
	v_lshl_add_u64 v[8:9], v[8:9], 0, s[16:17]
	global_load_dwordx4 v[132:135], v[8:9], off offset:-3072
	global_load_dwordx4 v[188:191], v[8:9], off offset:-2048
	global_load_dwordx4 v[192:195], v[8:9], off offset:-1024
	global_load_dwordx4 v[196:199], v[8:9], off
	v_lshl_add_u64 v[8:9], v[8:9], 0, s[16:17]
	global_load_dwordx4 v[200:203], v[8:9], off offset:-3072
	global_load_dwordx4 v[204:207], v[8:9], off offset:-2048
	global_load_dwordx4 v[236:239], v[8:9], off offset:-1024
	global_load_dwordx4 v[240:243], v[8:9], off
	s_waitcnt vmcnt(28)
	v_mul_f32_e32 v0, v37, v37
	v_mul_f32_e32 v3, v39, v39
	v_fmac_f32_e32 v0, v36, v36
	v_fmac_f32_e32 v3, v38, v38
	v_add_f32_e32 v16, v0, v3
	v_mul_f32_e32 v0, v41, v41
	v_mul_f32_e32 v3, v43, v43
	v_fmac_f32_e32 v0, v40, v40
	v_fmac_f32_e32 v3, v42, v42
	v_add_f32_e32 v0, v0, v3
	v_add_f32_e32 v16, v16, v0
	v_mul_f32_e32 v0, v45, v45
	v_mul_f32_e32 v3, v47, v47
	v_fmac_f32_e32 v0, v44, v44
	v_fmac_f32_e32 v3, v46, v46
	v_add_f32_e32 v0, v0, v3
	v_add_f32_e32 v16, v16, v0
	v_mul_f32_e32 v0, v49, v49
	v_mul_f32_e32 v3, v51, v51
	v_fmac_f32_e32 v0, v48, v48
	v_fmac_f32_e32 v3, v50, v50
	v_add_f32_e32 v0, v0, v3
	v_add_f32_e32 v16, v16, v0
	v_cvt_pk_bf16_f32 v36, v36, v37
	v_cvt_pk_bf16_f32 v37, v38, v39
	v_cvt_pk_bf16_f32 v40, v40, v41
	v_cvt_pk_bf16_f32 v41, v42, v43
	v_cvt_pk_bf16_f32 v44, v44, v45
	v_cvt_pk_bf16_f32 v45, v46, v47
	v_cvt_pk_bf16_f32 v48, v48, v49
	v_cvt_pk_bf16_f32 v49, v50, v51
	global_store_dwordx2 v[32:33], v[36:37], off
	global_store_dwordx2 v[32:33], v[40:41], off offset:512
	global_store_dwordx2 v[32:33], v[44:45], off offset:1024
	global_store_dwordx2 v[32:33], v[48:49], off offset:1536
	v_lshl_add_u64 v[32:33], v[32:33], 0, s[44:45]
	s_waitcnt vmcnt(28)
	v_mul_f32_e32 v0, v53, v53
	v_mul_f32_e32 v3, v55, v55
	v_fmac_f32_e32 v0, v52, v52
	v_fmac_f32_e32 v3, v54, v54
	v_add_f32_e32 v17, v0, v3
	v_mul_f32_e32 v0, v57, v57
	v_mul_f32_e32 v3, v59, v59
	v_fmac_f32_e32 v0, v56, v56
	v_fmac_f32_e32 v3, v58, v58
	v_add_f32_e32 v0, v0, v3
	v_add_f32_e32 v17, v17, v0
	v_mul_f32_e32 v0, v61, v61
	v_mul_f32_e32 v3, v63, v63
	v_fmac_f32_e32 v0, v60, v60
	v_fmac_f32_e32 v3, v62, v62
	v_add_f32_e32 v0, v0, v3
	v_add_f32_e32 v17, v17, v0
	v_mul_f32_e32 v0, v65, v65
	v_mul_f32_e32 v3, v67, v67
	v_fmac_f32_e32 v0, v64, v64
	v_fmac_f32_e32 v3, v66, v66
	v_add_f32_e32 v0, v0, v3
	v_add_f32_e32 v17, v17, v0
	v_cvt_pk_bf16_f32 v52, v52, v53
	v_cvt_pk_bf16_f32 v53, v54, v55
	v_cvt_pk_bf16_f32 v56, v56, v57
	v_cvt_pk_bf16_f32 v57, v58, v59
	v_cvt_pk_bf16_f32 v60, v60, v61
	v_cvt_pk_bf16_f32 v61, v62, v63
	v_cvt_pk_bf16_f32 v64, v64, v65
	v_cvt_pk_bf16_f32 v65, v66, v67
	global_store_dwordx2 v[32:33], v[52:53], off
	global_store_dwordx2 v[32:33], v[56:57], off offset:512
	global_store_dwordx2 v[32:33], v[60:61], off offset:1024
	global_store_dwordx2 v[32:33], v[64:65], off offset:1536
	v_lshl_add_u64 v[32:33], v[32:33], 0, s[44:45]
	s_waitcnt vmcnt(28)
	v_mul_f32_e32 v0, v69, v69
	v_mul_f32_e32 v3, v71, v71
	v_fmac_f32_e32 v0, v68, v68
	v_fmac_f32_e32 v3, v70, v70
	v_add_f32_e32 v18, v0, v3
	v_mul_f32_e32 v0, v73, v73
	v_mul_f32_e32 v3, v75, v75
	v_fmac_f32_e32 v0, v72, v72
	v_fmac_f32_e32 v3, v74, v74
	v_add_f32_e32 v0, v0, v3
	v_add_f32_e32 v18, v18, v0
	v_mul_f32_e32 v0, v77, v77
	v_mul_f32_e32 v3, v79, v79
	v_fmac_f32_e32 v0, v76, v76
	v_fmac_f32_e32 v3, v78, v78
	v_add_f32_e32 v0, v0, v3
	v_add_f32_e32 v18, v18, v0
	v_mul_f32_e32 v0, v81, v81
	v_mul_f32_e32 v3, v83, v83
	v_fmac_f32_e32 v0, v80, v80
	v_fmac_f32_e32 v3, v82, v82
	v_add_f32_e32 v0, v0, v3
	v_add_f32_e32 v18, v18, v0
	v_cvt_pk_bf16_f32 v68, v68, v69
	v_cvt_pk_bf16_f32 v69, v70, v71
	v_cvt_pk_bf16_f32 v72, v72, v73
	v_cvt_pk_bf16_f32 v73, v74, v75
	v_cvt_pk_bf16_f32 v76, v76, v77
	v_cvt_pk_bf16_f32 v77, v78, v79
	v_cvt_pk_bf16_f32 v80, v80, v81
	v_cvt_pk_bf16_f32 v81, v82, v83
	global_store_dwordx2 v[32:33], v[68:69], off
	global_store_dwordx2 v[32:33], v[72:73], off offset:512
	global_store_dwordx2 v[32:33], v[76:77], off offset:1024
	global_store_dwordx2 v[32:33], v[80:81], off offset:1536
	v_lshl_add_u64 v[32:33], v[32:33], 0, s[44:45]
	s_waitcnt vmcnt(28)
; DI void st_bf4(bf16_t* p, f32x4 v) { u32x2 w; w.x = pk2(v[0], v[1]); w.y = pk2(v[2], v[3]); *(u32x2*)p = w; }
;     DI bf16_t* hb() const { return (bf16_t*)(ws + WS_HB); }
;     DI float* ssqh() const { return (float*)(ws + WS_SSQH); }
;     DI const float* gin(int i) const { return (const float*)(const __attribute__((address_space(1))) float*)kp->in[i]; }
; DI void phase_prep(Frame& F) {
;     ...
;     for (int row = F.gw; row < M; row += F.ngw) {
;         const f32x4* xr = (const f32x4*)(F.gin(0) + (size_t)row * DM) + F.lane; float s = 0.f;
; #pragma unroll
;         for (int j = 0; j < 4; ++j) { f32x4 v = xr[64 * j]; s += (v[0] * v[0] + v[1] * v[1]) + (v[2] * v[2] + v[3] * v[3]);
;             st_bf4(F.hb() + (size_t)row * DM + 4 * (F.lane + 64 * j), v); }
;         s = wave_sum(s);
;         if (F.lane < 16) F.ssqh()[(size_t)row * 16 + F.lane] = F.lane == 0 ? s : 0.f;
	v_mul_f32_e32 v0, v85, v85
	v_mul_f32_e32 v3, v87, v87
	v_fmac_f32_e32 v0, v84, v84
	v_fmac_f32_e32 v3, v86, v86
	v_add_f32_e32 v19, v0, v3
	v_mul_f32_e32 v0, v89, v89
	v_mul_f32_e32 v3, v91, v91
	v_fmac_f32_e32 v0, v88, v88
	v_fmac_f32_e32 v3, v90, v90
	v_add_f32_e32 v0, v0, v3
	v_add_f32_e32 v19, v19, v0
	v_mul_f32_e32 v0, v93, v93
	v_mul_f32_e32 v3, v95, v95
	v_fmac_f32_e32 v0, v92, v92
	v_fmac_f32_e32 v3, v94, v94
	v_add_f32_e32 v0, v0, v3
	v_add_f32_e32 v19, v19, v0
	v_mul_f32_e32 v0, v97, v97
	v_mul_f32_e32 v3, v99, v99
	v_fmac_f32_e32 v0, v96, v96
	v_fmac_f32_e32 v3, v98, v98
	v_add_f32_e32 v0, v0, v3
	v_add_f32_e32 v19, v19, v0
	v_cvt_pk_bf16_f32 v84, v84, v85
	v_cvt_pk_bf16_f32 v85, v86, v87
	v_cvt_pk_bf16_f32 v88, v88, v89
	v_cvt_pk_bf16_f32 v89, v90, v91
	v_cvt_pk_bf16_f32 v92, v92, v93
	v_cvt_pk_bf16_f32 v93, v94, v95
	v_cvt_pk_bf16_f32 v96, v96, v97
	v_cvt_pk_bf16_f32 v97, v98, v99
	global_store_dwordx2 v[32:33], v[84:85], off
	global_store_dwordx2 v[32:33], v[88:89], off offset:512
	global_store_dwordx2 v[32:33], v[92:93], off offset:1024
	global_store_dwordx2 v[32:33], v[96:97], off offset:1536
	v_lshl_add_u64 v[32:33], v[32:33], 0, s[44:45]
	s_waitcnt vmcnt(28)
	v_mul_f32_e32 v0, v101, v101
	v_mul_f32_e32 v3, v103, v103
	v_fmac_f32_e32 v0, v100, v100
	v_fmac_f32_e32 v3, v102, v102
	v_add_f32_e32 v20, v0, v3
	v_mul_f32_e32 v0, v105, v105
	v_mul_f32_e32 v3, v107, v107
	v_fmac_f32_e32 v0, v104, v104
	v_fmac_f32_e32 v3, v106, v106
	v_add_f32_e32 v0, v0, v3
	v_add_f32_e32 v20, v20, v0
	v_mul_f32_e32 v0, v109, v109
	v_mul_f32_e32 v3, v111, v111
	v_fmac_f32_e32 v0, v108, v108
	v_fmac_f32_e32 v3, v110, v110
	v_add_f32_e32 v0, v0, v3
	v_add_f32_e32 v20, v20, v0
	v_mul_f32_e32 v0, v113, v113
	v_mul_f32_e32 v3, v115, v115
	v_fmac_f32_e32 v0, v112, v112
	v_fmac_f32_e32 v3, v114, v114
	v_add_f32_e32 v0, v0, v3
	v_add_f32_e32 v20, v20, v0
	v_cvt_pk_bf16_f32 v100, v100, v101
	v_cvt_pk_bf16_f32 v101, v102, v103
	v_cvt_pk_bf16_f32 v104, v104, v105
	v_cvt_pk_bf16_f32 v105, v106, v107
	v_cvt_pk_bf16_f32 v108, v108, v109
	v_cvt_pk_bf16_f32 v109, v110, v111
	v_cvt_pk_bf16_f32 v112, v112, v113
	v_cvt_pk_bf16_f32 v113, v114, v115
	global_store_dwordx2 v[32:33], v[100:101], off
	global_store_dwordx2 v[32:33], v[104:105], off offset:512
	global_store_dwordx2 v[32:33], v[108:109], off offset:1024
	global_store_dwordx2 v[32:33], v[112:113], off offset:1536
	v_lshl_add_u64 v[32:33], v[32:33], 0, s[44:45]
	s_waitcnt vmcnt(28)
	v_mul_f32_e32 v0, v117, v117
	v_mul_f32_e32 v3, v119, v119
	v_fmac_f32_e32 v0, v116, v116
	v_fmac_f32_e32 v3, v118, v118
	v_add_f32_e32 v21, v0, v3
	v_mul_f32_e32 v0, v121, v121
	v_mul_f32_e32 v3, v123, v123
	v_fmac_f32_e32 v0, v120, v120
	v_fmac_f32_e32 v3, v122, v122
	v_add_f32_e32 v0, v0, v3
	v_add_f32_e32 v21, v21, v0
	v_mul_f32_e32 v0, v125, v125
	v_mul_f32_e32 v3, v127, v127
	v_fmac_f32_e32 v0, v124, v124
	v_fmac_f32_e32 v3, v126, v126
	v_add_f32_e32 v0, v0, v3
	v_add_f32_e32 v21, v21, v0
	v_mul_f32_e32 v0, v129, v129
	v_mul_f32_e32 v3, v131, v131
	v_fmac_f32_e32 v0, v128, v128
	v_fmac_f32_e32 v3, v130, v130
	v_add_f32_e32 v0, v0, v3
	v_add_f32_e32 v21, v21, v0
	v_cvt_pk_bf16_f32 v116, v116, v117
	v_cvt_pk_bf16_f32 v117, v118, v119
	v_cvt_pk_bf16_f32 v120, v120, v121
	v_cvt_pk_bf16_f32 v121, v122, v123
	v_cvt_pk_bf16_f32 v124, v124, v125
	v_cvt_pk_bf16_f32 v125, v126, v127
	v_cvt_pk_bf16_f32 v128, v128, v129
	v_cvt_pk_bf16_f32 v129, v130, v131
	global_store_dwordx2 v[32:33], v[116:117], off
	global_store_dwordx2 v[32:33], v[120:121], off offset:512
	global_store_dwordx2 v[32:33], v[124:125], off offset:1024
	global_store_dwordx2 v[32:33], v[128:129], off offset:1536
	v_lshl_add_u64 v[32:33], v[32:33], 0, s[44:45]
	s_waitcnt vmcnt(28)
	v_mul_f32_e32 v0, v133, v133
	v_mul_f32_e32 v3, v135, v135
	v_fmac_f32_e32 v0, v132, v132
	v_fmac_f32_e32 v3, v134, v134
	v_add_f32_e32 v22, v0, v3
	v_mul_f32_e32 v0, v189, v189
	v_mul_f32_e32 v3, v191, v191
	v_fmac_f32_e32 v0, v188, v188
	v_fmac_f32_e32 v3, v190, v190
	v_add_f32_e32 v0, v0, v3
	v_add_f32_e32 v22, v22, v0
	v_mul_f32_e32 v0, v193, v193
	v_mul_f32_e32 v3, v195, v195
	v_fmac_f32_e32 v0, v192, v192
	v_fmac_f32_e32 v3, v194, v194
	v_add_f32_e32 v0, v0, v3
	v_add_f32_e32 v22, v22, v0
	v_mul_f32_e32 v0, v197, v197
	v_mul_f32_e32 v3, v199, v199
	v_fmac_f32_e32 v0, v196, v196
	v_fmac_f32_e32 v3, v198, v198
	v_add_f32_e32 v0, v0, v3
	v_add_f32_e32 v22, v22, v0
	v_cvt_pk_bf16_f32 v132, v132, v133
	v_cvt_pk_bf16_f32 v133, v134, v135
	v_cvt_pk_bf16_f32 v188, v188, v189
	v_cvt_pk_bf16_f32 v189, v190, v191
	v_cvt_pk_bf16_f32 v192, v192, v193
	v_cvt_pk_bf16_f32 v193, v194, v195
	v_cvt_pk_bf16_f32 v196, v196, v197
	v_cvt_pk_bf16_f32 v197, v198, v199
	global_store_dwordx2 v[32:33], v[132:133], off
	global_store_dwordx2 v[32:33], v[188:189], off offset:512
	global_store_dwordx2 v[32:33], v[192:193], off offset:1024
	global_store_dwordx2 v[32:33], v[196:197], off offset:1536
	v_lshl_add_u64 v[32:33], v[32:33], 0, s[44:45]
	s_waitcnt vmcnt(28)
; DI void st_bf4(bf16_t* p, f32x4 v) { u32x2 w; w.x = pk2(v[0], v[1]); w.y = pk2(v[2], v[3]); *(u32x2*)p = w; }
;     DI bf16_t* hb() const { return (bf16_t*)(ws + WS_HB); }
;     DI float* ssqh() const { return (float*)(ws + WS_SSQH); }
;     DI const float* gin(int i) const { return (const float*)(const __attribute__((address_space(1))) float*)kp->in[i]; }
; DI float wave_sum(float v) {
; #pragma unroll
;     for (int o = 1; o < 64; o <<= 1) v += __shfl_xor(v, o);
;     return v;
; }
; DI void phase_prep(Frame& F) {
;     ...
;     for (int row = F.gw; row < M; row += F.ngw) {
;         const f32x4* xr = (const f32x4*)(F.gin(0) + (size_t)row * DM) + F.lane; float s = 0.f;
; #pragma unroll
;         for (int j = 0; j < 4; ++j) { f32x4 v = xr[64 * j]; s += (v[0] * v[0] + v[1] * v[1]) + (v[2] * v[2] + v[3] * v[3]);
;             st_bf4(F.hb() + (size_t)row * DM + 4 * (F.lane + 64 * j), v); }
;         s = wave_sum(s);
;         if (F.lane < 16) F.ssqh()[(size_t)row * 16 + F.lane] = F.lane == 0 ? s : 0.f;
	v_mul_f32_e32 v0, v201, v201
	v_mul_f32_e32 v3, v203, v203
	v_fmac_f32_e32 v0, v200, v200
	v_fmac_f32_e32 v3, v202, v202
	v_add_f32_e32 v23, v0, v3
	v_mul_f32_e32 v0, v205, v205
	v_mul_f32_e32 v3, v207, v207
	v_fmac_f32_e32 v0, v204, v204
	v_fmac_f32_e32 v3, v206, v206
	v_add_f32_e32 v0, v0, v3
	v_add_f32_e32 v23, v23, v0
	v_mul_f32_e32 v0, v237, v237
	v_mul_f32_e32 v3, v239, v239
	v_fmac_f32_e32 v0, v236, v236
	v_fmac_f32_e32 v3, v238, v238
	v_add_f32_e32 v0, v0, v3
	v_add_f32_e32 v23, v23, v0
	v_mul_f32_e32 v0, v241, v241
	v_mul_f32_e32 v3, v243, v243
	v_fmac_f32_e32 v0, v240, v240
	v_fmac_f32_e32 v3, v242, v242
	v_add_f32_e32 v0, v0, v3
	v_add_f32_e32 v23, v23, v0
	v_cvt_pk_bf16_f32 v200, v200, v201
	v_cvt_pk_bf16_f32 v201, v202, v203
	v_cvt_pk_bf16_f32 v204, v204, v205
	v_cvt_pk_bf16_f32 v205, v206, v207
	v_cvt_pk_bf16_f32 v236, v236, v237
	v_cvt_pk_bf16_f32 v237, v238, v239
	v_cvt_pk_bf16_f32 v240, v240, v241
	v_cvt_pk_bf16_f32 v241, v242, v243
	global_store_dwordx2 v[32:33], v[200:201], off
	global_store_dwordx2 v[32:33], v[204:205], off offset:512
	global_store_dwordx2 v[32:33], v[236:237], off offset:1024
	global_store_dwordx2 v[32:33], v[240:241], off offset:1536
	ds_bpermute_b32 v24, v10, v16
	ds_bpermute_b32 v25, v10, v17
	ds_bpermute_b32 v26, v10, v18
	ds_bpermute_b32 v27, v10, v19
	ds_bpermute_b32 v28, v10, v20
	ds_bpermute_b32 v29, v10, v21
	ds_bpermute_b32 v30, v10, v22
	ds_bpermute_b32 v31, v10, v23
	s_waitcnt lgkmcnt(0)
	v_add_f32_e32 v16, v16, v24
	v_add_f32_e32 v17, v17, v25
	v_add_f32_e32 v18, v18, v26
	v_add_f32_e32 v19, v19, v27
	v_add_f32_e32 v20, v20, v28
	v_add_f32_e32 v21, v21, v29
	v_add_f32_e32 v22, v22, v30
	v_add_f32_e32 v23, v23, v31
	ds_bpermute_b32 v24, v11, v16
	ds_bpermute_b32 v25, v11, v17
	ds_bpermute_b32 v26, v11, v18
	ds_bpermute_b32 v27, v11, v19
	ds_bpermute_b32 v28, v11, v20
	ds_bpermute_b32 v29, v11, v21
	ds_bpermute_b32 v30, v11, v22
	ds_bpermute_b32 v31, v11, v23
	s_waitcnt lgkmcnt(0)
	v_add_f32_e32 v16, v16, v24
	v_add_f32_e32 v17, v17, v25
	v_add_f32_e32 v18, v18, v26
	v_add_f32_e32 v19, v19, v27
	v_add_f32_e32 v20, v20, v28
	v_add_f32_e32 v21, v21, v29
	v_add_f32_e32 v22, v22, v30
	v_add_f32_e32 v23, v23, v31
	ds_bpermute_b32 v24, v12, v16
	ds_bpermute_b32 v25, v12, v17
	ds_bpermute_b32 v26, v12, v18
	ds_bpermute_b32 v27, v12, v19
	ds_bpermute_b32 v28, v12, v20
	ds_bpermute_b32 v29, v12, v21
	ds_bpermute_b32 v30, v12, v22
	ds_bpermute_b32 v31, v12, v23
	s_waitcnt lgkmcnt(0)
	v_add_f32_e32 v16, v16, v24
	v_add_f32_e32 v17, v17, v25
	v_add_f32_e32 v18, v18, v26
	v_add_f32_e32 v19, v19, v27
	v_add_f32_e32 v20, v20, v28
	v_add_f32_e32 v21, v21, v29
	v_add_f32_e32 v22, v22, v30
	v_add_f32_e32 v23, v23, v31
	ds_bpermute_b32 v24, v13, v16
	ds_bpermute_b32 v25, v13, v17
	ds_bpermute_b32 v26, v13, v18
	ds_bpermute_b32 v27, v13, v19
	ds_bpermute_b32 v28, v13, v20
	ds_bpermute_b32 v29, v13, v21
	ds_bpermute_b32 v30, v13, v22
	ds_bpermute_b32 v31, v13, v23
	s_waitcnt lgkmcnt(0)
	v_add_f32_e32 v16, v16, v24
	v_add_f32_e32 v17, v17, v25
	v_add_f32_e32 v18, v18, v26
	v_add_f32_e32 v19, v19, v27
	v_add_f32_e32 v20, v20, v28
	v_add_f32_e32 v21, v21, v29
	v_add_f32_e32 v22, v22, v30
	v_add_f32_e32 v23, v23, v31
	ds_bpermute_b32 v24, v14, v16
	ds_bpermute_b32 v25, v14, v17
	ds_bpermute_b32 v26, v14, v18
	ds_bpermute_b32 v27, v14, v19
	ds_bpermute_b32 v28, v14, v20
	ds_bpermute_b32 v29, v14, v21
	ds_bpermute_b32 v30, v14, v22
	ds_bpermute_b32 v31, v14, v23
	s_waitcnt lgkmcnt(0)
	v_add_f32_e32 v16, v16, v24
	v_add_f32_e32 v17, v17, v25
	v_add_f32_e32 v18, v18, v26
	v_add_f32_e32 v19, v19, v27
	v_add_f32_e32 v20, v20, v28
	v_add_f32_e32 v21, v21, v29
	v_add_f32_e32 v22, v22, v30
	v_add_f32_e32 v23, v23, v31
	ds_bpermute_b32 v24, v15, v16
	ds_bpermute_b32 v25, v15, v17
	ds_bpermute_b32 v26, v15, v18
	ds_bpermute_b32 v27, v15, v19
	ds_bpermute_b32 v28, v15, v20
	ds_bpermute_b32 v29, v15, v21
	ds_bpermute_b32 v30, v15, v22
	ds_bpermute_b32 v31, v15, v23
	s_waitcnt lgkmcnt(0)
	v_add_f32_e32 v16, v16, v24
	v_add_f32_e32 v17, v17, v25
	v_add_f32_e32 v18, v18, v26
	v_add_f32_e32 v19, v19, v27
	v_add_f32_e32 v20, v20, v28
	v_add_f32_e32 v21, v21, v29
	v_add_f32_e32 v22, v22, v30
	v_add_f32_e32 v23, v23, v31
	v_cndmask_b32_e64 v16, 0, v16, s[42:43]
	v_cndmask_b32_e64 v17, 0, v17, s[42:43]
	v_cndmask_b32_e64 v18, 0, v18, s[42:43]
	v_cndmask_b32_e64 v19, 0, v19, s[42:43]
	v_cndmask_b32_e64 v20, 0, v20, s[42:43]
	v_cndmask_b32_e64 v21, 0, v21, s[42:43]
	v_cndmask_b32_e64 v22, 0, v22, s[42:43]
	v_cndmask_b32_e64 v23, 0, v23, s[42:43]
	s_and_saveexec_b64 s[24:25], vcc
	global_store_dword v[210:211], v16, off
	v_lshl_add_u64 v[210:211], v[210:211], 0, s[10:11]
	global_store_dword v[210:211], v17, off
	v_lshl_add_u64 v[210:211], v[210:211], 0, s[10:11]
	global_store_dword v[210:211], v18, off
	v_lshl_add_u64 v[210:211], v[210:211], 0, s[10:11]
	global_store_dword v[210:211], v19, off
	v_lshl_add_u64 v[210:211], v[210:211], 0, s[10:11]
	global_store_dword v[210:211], v20, off
	v_lshl_add_u64 v[210:211], v[210:211], 0, s[10:11]
	global_store_dword v[210:211], v21, off
	v_lshl_add_u64 v[210:211], v[210:211], 0, s[10:11]
	global_store_dword v[210:211], v22, off
	v_lshl_add_u64 v[210:211], v[210:211], 0, s[10:11]
	global_store_dword v[210:211], v23, off
	s_or_b64 exec, exec, s[24:25]
